# P0 weight-transpose loops: per-item flat pointer reload + vmcnt(0) replaced by s_load + lgkmcnt(0) (previous item's stores no longer block the next item's loads)
# baseline (speedup 1.0000x reference)
; #define LAS __attribute__((address_space(3)))
; __device__ __forceinline__ void transpose_item(const float* W, int K, int N, bf16_t* WT, LAS float* scr, int item, int lane) {
;     const int nblk = (N + 31) / 32, kb = item / nblk, nb = item % nblk, k0 = 64 * kb, n0 = 32 * nb;
;     const int nn = n0 + (lane & 31); const bool ok = nn < N;
;     float v[32];
; #pragma unroll
;     for (int i = 0; i < 32; ++i) { const int kk = 2 * i + (lane >> 5); v[i] = ok ? W[(size_t)(k0 + kk) * N + nn] : 0.f; }
; __global__ void __launch_bounds__(512, 2) mega(Args a) {
;     ...
;         for (int it = gw; it < 4 * I_ADA; it += NGW) { const int l = it / I_ADA, r = it - l * I_ADA;
;             transpose_item(((const float*)ap->in[8]) + (size_t)l * DM * 3 * DM, DM, 3 * DM, WSP(bf16_t, WS_WADA) + (size_t)l * 3 * DM * DM, scr, r, lane); }
.LBB0_8:
	s_load_dwordx2 s[98:99], s[0:1], 0x40
	s_mul_hi_i32 s8, s14, 0x2aaaaaab
	s_lshr_b32 s9, s8, 31
	s_ashr_i32 s8, s8, 10
	s_add_i32 s9, s8, s9
	s_mul_i32 s8, s9, 0xffffe800
	s_add_i32 s10, s14, s8
	s_mul_hi_i32 s8, s10, 0x2aaaaaab
	s_lshr_b32 s11, s8, 31
	s_ashr_i32 s8, s8, 5
	s_add_i32 s8, s8, s11
	s_mul_i32 s11, s8, 0xc0
	s_sub_i32 s10, s10, s11
	s_lshl_b32 s17, s10, 5
	v_or_b32_e32 v24, s17, v13
	s_lshl_b32 s8, s8, 6
	v_ashrrev_i32_e32 v25, 31, v24
	v_or_b32_e32 v23, s8, v14
	v_cmp_gt_i32_e32 vcc, s15, v24
	s_waitcnt lgkmcnt(0)
	v_mov_b32_e32 v10, s98
	v_mov_b32_e32 v11, s99
	v_mad_i64_i32 v[10:11], s[10:11], s9, v20, v[10:11]
	v_lshl_add_u64 v[10:11], v[24:25], 2, v[10:11]
	v_mov_b32_e32 v24, 0
	s_and_saveexec_b64 s[10:11], vcc
	s_cbranch_execz .LBB0_10
	v_mad_i64_i32 v[24:25], s[18:19], v23, s16, v[10:11]
	global_load_dword v24, v[24:25], off

; #define LAS __attribute__((address_space(3)))
; __device__ __forceinline__ void transpose_item(const float* W, int K, int N, bf16_t* WT, LAS float* scr, int item, int lane) {
;     const int nblk = (N + 31) / 32, kb = item / nblk, nb = item % nblk, k0 = 64 * kb, n0 = 32 * nb;
;     const int nn = n0 + (lane & 31); const bool ok = nn < N;
;     float v[32];
; #pragma unroll
;     for (int i = 0; i < 32; ++i) { const int kk = 2 * i + (lane >> 5); v[i] = ok ? W[(size_t)(k0 + kk) * N + nn] : 0.f; }
; __global__ void __launch_bounds__(512, 2) mega(Args a) {
;     ...
;             else { r -= 4 * I_IN; const int l = r / I_OUT; r -= l * I_OUT; transpose_item(((const float*)ap->in[16]) + (size_t)l * DM * DM, DM, DM, WSP(bf16_t, WS_WOUT) + (size_t)l * DM * DM, scr, r, lane); }
.LBB0_156:
	v_mov_b64_e32 v[4:5], s[6:7]
	s_load_dwordx2 s[98:99], s[0:1], 0x80
	s_add_i32 s9, s13, 0xffff7f80
	s_and_b32 s8, s16, 0x7e0
	s_and_b32 s4, s9, 0xfffff800
	s_and_b32 s9, s9, 0x7c0
	v_or_b32_e32 v23, s8, v6
	s_lshl_b64 s[10:11], s[4:5], 13
	v_mov_b32_e32 v25, v3
	v_or_b32_e32 v26, s9, v7
	v_lshlrev_b32_e32 v24, 2, v23
	v_mov_b32_e32 v27, v3
	v_lshlrev_b32_e32 v26, 13, v26
	s_waitcnt lgkmcnt(0)
	v_mov_b32_e32 v4, s98
	v_mov_b32_e32 v5, s99
	v_lshl_add_u64 v[4:5], v[4:5], 0, s[10:11]
	v_lshl_add_u64 v[4:5], v[4:5], 0, v[24:25]
	v_lshl_add_u64 v[4:5], v[4:5], 0, v[26:27]
	v_add_co_u32_e32 v24, vcc, s18, v4
	s_lshl_b64 s[10:11], s[4:5], 12
	s_nop 0
	v_addc_co_u32_e32 v25, vcc, 0, v5, vcc
	v_add_co_u32_e32 v26, vcc, s19, v4
	s_lshl_b32 s4, s9, 1
	s_nop 0
	v_addc_co_u32_e32 v27, vcc, 0, v5, vcc
	v_add_co_u32_e32 v28, vcc, s20, v4
	s_nop 1
	v_addc_co_u32_e32 v29, vcc, 0, v5, vcc
	v_add_co_u32_e32 v30, vcc, s21, v4
	s_nop 1
	v_addc_co_u32_e32 v31, vcc, 0, v5, vcc
	v_add_co_u32_e32 v32, vcc, s22, v4
	s_nop 1
	v_addc_co_u32_e32 v33, vcc, 0, v5, vcc
	v_add_co_u32_e32 v34, vcc, s23, v4
	s_nop 1
	v_addc_co_u32_e32 v35, vcc, 0, v5, vcc
	v_add_co_u32_e32 v36, vcc, s24, v4
	s_nop 1
	v_addc_co_u32_e32 v37, vcc, 0, v5, vcc
	v_add_co_u32_e32 v38, vcc, s25, v4
	s_nop 1
	v_addc_co_u32_e32 v39, vcc, 0, v5, vcc
	v_add_co_u32_e32 v40, vcc, s26, v4
	s_nop 1
	v_addc_co_u32_e32 v41, vcc, 0, v5, vcc
	v_add_co_u32_e32 v42, vcc, s27, v4
	s_nop 1
	v_addc_co_u32_e32 v43, vcc, 0, v5, vcc
	v_add_co_u32_e32 v44, vcc, s28, v4
	s_nop 1
	v_addc_co_u32_e32 v45, vcc, 0, v5, vcc
	v_add_co_u32_e32 v46, vcc, s29, v4
	s_nop 1
	v_addc_co_u32_e32 v47, vcc, 0, v5, vcc
	v_add_co_u32_e32 v48, vcc, s30, v4
	s_nop 1
	v_addc_co_u32_e32 v49, vcc, 0, v5, vcc
	v_add_co_u32_e32 v50, vcc, s31, v4
	s_nop 1
	v_addc_co_u32_e32 v51, vcc, 0, v5, vcc
	v_add_co_u32_e32 v52, vcc, s33, v4
	s_nop 1
	v_addc_co_u32_e32 v53, vcc, 0, v5, vcc
	global_load_dword v23, v[4:5], off
	global_load_dword v54, v[24:25], off
	global_load_dword v55, v[26:27], off
	global_load_dword v56, v[28:29], off
	global_load_dword v57, v[30:31], off
	global_load_dword v58, v[32:33], off
	global_load_dword v59, v[34:35], off
	global_load_dword v60, v[36:37], off
	global_load_dword v61, v[38:39], off
	s_nop 0
	global_load_dword v40, v[40:41], off
	s_nop 0
	global_load_dword v41, v[42:43], off
	s_nop 0
	global_load_dword v42, v[44:45], off
	global_load_dword v43, v[46:47], off
	s_nop 0
	global_load_dword v44, v[48:49], off
	global_load_dword v45, v[50:51], off
	global_load_dword v46, v[52:53], off
	v_add_co_u32_e32 v24, vcc, s34, v4
	s_nop 1
	v_addc_co_u32_e32 v25, vcc, 0, v5, vcc
	v_add_co_u32_e32 v26, vcc, s35, v4
	s_nop 1
	v_addc_co_u32_e32 v27, vcc, 0, v5, vcc
	v_add_co_u32_e32 v28, vcc, s36, v4
	s_nop 1
	v_addc_co_u32_e32 v29, vcc, 0, v5, vcc
	v_add_co_u32_e32 v30, vcc, s37, v4
	s_nop 1
	v_addc_co_u32_e32 v31, vcc, 0, v5, vcc
	v_add_co_u32_e32 v32, vcc, s40, v4
	s_nop 1
	v_addc_co_u32_e32 v33, vcc, 0, v5, vcc
	v_add_co_u32_e32 v34, vcc, s41, v4
	s_nop 1
	v_addc_co_u32_e32 v35, vcc, 0, v5, vcc
	v_add_co_u32_e32 v36, vcc, s42, v4
	s_nop 1
	v_addc_co_u32_e32 v37, vcc, 0, v5, vcc
	v_add_co_u32_e32 v38, vcc, s43, v4
	s_nop 1
	v_addc_co_u32_e32 v39, vcc, 0, v5, vcc
	global_load_dword v47, v[24:25], off
	global_load_dword v48, v[26:27], off
	global_load_dword v49, v[28:29], off
	global_load_dword v50, v[30:31], off
	global_load_dword v51, v[32:33], off
	global_load_dword v52, v[34:35], off
	global_load_dword v53, v[36:37], off
	s_nop 0
	global_load_dword v38, v[38:39], off
	v_add_co_u32_e32 v24, vcc, s44, v4
	s_nop 1
	v_addc_co_u32_e32 v25, vcc, 0, v5, vcc
	v_add_co_u32_e32 v26, vcc, s45, v4
	s_nop 1
	v_addc_co_u32_e32 v27, vcc, 0, v5, vcc
	v_add_co_u32_e32 v28, vcc, s46, v4
	s_nop 1
	v_addc_co_u32_e32 v29, vcc, 0, v5, vcc
	v_add_co_u32_e32 v30, vcc, s47, v4
	s_nop 1
	v_addc_co_u32_e32 v31, vcc, 0, v5, vcc
	v_add_co_u32_e32 v32, vcc, s48, v4
	s_nop 1
	v_addc_co_u32_e32 v33, vcc, 0, v5, vcc
	v_add_co_u32_e32 v34, vcc, s49, v4
	s_nop 1
	v_addc_co_u32_e32 v35, vcc, 0, v5, vcc
	v_add_co_u32_e32 v36, vcc, s50, v4
	s_nop 1
	v_addc_co_u32_e32 v37, vcc, 0, v5, vcc
	v_add_co_u32_e32 v4, vcc, s51, v4
	s_nop 1
	v_addc_co_u32_e32 v5, vcc, 0, v5, vcc
	global_load_dword v24, v[24:25], off
	s_nop 0
	global_load_dword v25, v[26:27], off
	s_nop 0
	global_load_dword v26, v[28:29], off
	global_load_dword v27, v[30:31], off
	s_nop 0
	global_load_dword v28, v[32:33], off
	global_load_dword v29, v[34:35], off
	global_load_dword v30, v[36:37], off
	global_load_dword v31, v[4:5], off
	s_waitcnt vmcnt(30)
; #define LAS __attribute__((address_space(3)))
; __device__ __forceinline__ unsigned pk2(float lo, float hi) { return pg8::cvt_pk_bf16(lo, hi); }
; #define LDS_WAIT() asm volatile("s_waitcnt lgkmcnt(0)" ::: "memory")
; __device__ __forceinline__ void transpose_item(const float* W, int K, int N, bf16_t* WT, LAS float* scr, int item, int lane) {
;     const int nblk = (N + 31) / 32, kb = item / nblk, nb = item % nblk, k0 = 64 * kb, n0 = 32 * nb;
;     const int nn = n0 + (lane & 31); const bool ok = nn < N;
;     float v[32];
; #pragma unroll
;     for (int i = 0; i < 32; ++i) { const int kk = 2 * i + (lane >> 5); v[i] = ok ? W[(size_t)(k0 + kk) * N + nn] : 0.f; }
; #pragma unroll
;     for (int i = 0; i < 32; ++i) { const int kk = 2 * i + (lane >> 5); scr[kk * 33 + (lane & 31)] = v[i]; }
;     LDS_WAIT(); asm volatile("" ::: "memory");
;     const int c = lane & 7;
; #pragma unroll
;     for (int j = 0; j < 4; ++j) { const int n = (lane >> 3) + 8 * j; const LAS float* s = scr + (8 * c) * 33 + n;
;         u32x4 o; o.x = pk2(s[0 * 33], s[1 * 33]); o.y = pk2(s[2 * 33], s[3 * 33]); o.z = pk2(s[4 * 33], s[5 * 33]); o.w = pk2(s[6 * 33], s[7 * 33]);
;         *(u32x4*)(WT + (size_t)(n0 + n) * K + k0 + 8 * c) = o; }
;     LDS_WAIT(); asm volatile("" ::: "memory");
; }
; __global__ void __launch_bounds__(512, 2) mega(Args a) {
;     ...
;             if (r < 4 * I_IN) { const int l = r / I_IN; r -= l * I_IN; transpose_item(((const float*)ap->in[10]) + (size_t)l * DM * DIN, DM, DIN, WSP(bf16_t, WS_WIN) + (size_t)l * DINP * DM, scr, r, lane); }
	ds_write2_b32 v13, v23, v54 offset1:66
	s_waitcnt vmcnt(28)
	ds_write2_b32 v13, v55, v56 offset0:132 offset1:198
	s_waitcnt vmcnt(26)
	ds_write2_b32 v14, v57, v58 offset0:8 offset1:74
	s_waitcnt vmcnt(24)
	ds_write2_b32 v14, v59, v60 offset0:140 offset1:206
	s_waitcnt vmcnt(22)
	ds_write2_b32 v15, v61, v40 offset0:16 offset1:82
	s_waitcnt vmcnt(20)
	ds_write2_b32 v15, v41, v42 offset0:148 offset1:214
	s_waitcnt vmcnt(18)
	ds_write2_b32 v16, v43, v44 offset0:24 offset1:90
	s_waitcnt vmcnt(16)
	ds_write2_b32 v16, v45, v46 offset0:156 offset1:222
	s_waitcnt vmcnt(14)
	ds_write2_b32 v17, v47, v48 offset0:32 offset1:98
	s_waitcnt vmcnt(12)
	ds_write2_b32 v17, v49, v50 offset0:164 offset1:230
	s_waitcnt vmcnt(10)
	ds_write2_b32 v18, v51, v52 offset0:40 offset1:106
	s_waitcnt vmcnt(8)
	ds_write2_b32 v18, v53, v38 offset0:172 offset1:238
	s_waitcnt vmcnt(6)
	ds_write2_b32 v19, v24, v25 offset0:48 offset1:114
	s_waitcnt vmcnt(4)
	ds_write2_b32 v19, v26, v27 offset0:180 offset1:246
	s_waitcnt vmcnt(2)
	ds_write2_b32 v20, v28, v29 offset0:56 offset1:122
	s_waitcnt vmcnt(0)
	ds_write2_b32 v20, v30, v31 offset0:188 offset1:254
	s_waitcnt lgkmcnt(0)
	ds_read2_b32 v[28:29], v9 offset0:33 offset1:41
	ds_read2_b32 v[30:31], v9 offset1:8
	ds_read2_b32 v[32:33], v9 offset0:66 offset1:74
	ds_read2_b32 v[34:35], v9 offset0:99 offset1:107
	ds_read2_b32 v[36:37], v9 offset0:132 offset1:140
	ds_read2_b32 v[38:39], v9 offset0:165 offset1:173
	ds_read2_b32 v[40:41], v9 offset0:198 offset1:206
	ds_read2_b32 v[42:43], v9 offset0:231 offset1:239
	v_lshl_add_u64 v[4:5], v[0:1], 0, s[10:11]
	v_lshl_add_u64 v[4:5], v[4:5], 0, s[4:5]
	v_or_b32_e32 v23, s8, v8
	v_lshl_add_u64 v[4:5], v[4:5], 0, v[2:3]
	v_lshlrev_b32_e32 v44, 12, v23
	v_mov_b32_e32 v45, v3
	v_lshl_add_u64 v[44:45], v[4:5], 0, v[44:45]
	s_waitcnt lgkmcnt(6)
	v_cvt_pk_bf16_f32 v24, v30, v28
	s_waitcnt lgkmcnt(4)
	v_cvt_pk_bf16_f32 v25, v32, v34
	s_waitcnt lgkmcnt(2)
	v_cvt_pk_bf16_f32 v26, v36, v38
	s_waitcnt lgkmcnt(0)
	v_cvt_pk_bf16_f32 v27, v40, v42
	global_store_dwordx4 v[44:45], v[24:27], off
	v_or_b32_e32 v23, s8, v10
	v_lshlrev_b32_e32 v28, 12, v23
	v_cvt_pk_bf16_f32 v24, v31, v29
	v_cvt_pk_bf16_f32 v25, v33, v35
	v_cvt_pk_bf16_f32 v26, v37, v39
	v_cvt_pk_bf16_f32 v27, v41, v43
	ds_read2_b32 v[30:31], v9 offset0:16 offset1:24
	ds_read2_b32 v[32:33], v9 offset0:49 offset1:57
	ds_read2_b32 v[34:35], v9 offset0:82 offset1:90
	ds_read2_b32 v[36:37], v9 offset0:115 offset1:123
	ds_read2_b32 v[38:39], v9 offset0:148 offset1:156
	ds_read2_b32 v[40:41], v9 offset0:181 offset1:189
	ds_read2_b32 v[42:43], v9 offset0:214 offset1:222
	ds_read2_b32 v[44:45], v9 offset0:247 offset1:255
	v_mov_b32_e32 v29, v3
	v_lshl_add_u64 v[28:29], v[4:5], 0, v[28:29]
	v_or_b32_e32 v23, s8, v11
	global_store_dwordx4 v[28:29], v[24:27], off
	v_lshlrev_b32_e32 v28, 12, v23
	v_mov_b32_e32 v29, v3
	v_lshl_add_u64 v[28:29], v[4:5], 0, v[28:29]
	v_or_b32_e32 v23, s8, v12
	s_waitcnt lgkmcnt(6)
	v_cvt_pk_bf16_f32 v24, v30, v32
	s_waitcnt lgkmcnt(4)
	v_cvt_pk_bf16_f32 v25, v34, v36
	s_waitcnt lgkmcnt(2)
	v_cvt_pk_bf16_f32 v26, v38, v40
	s_waitcnt lgkmcnt(0)
	v_cvt_pk_bf16_f32 v27, v42, v44
	global_store_dwordx4 v[28:29], v[24:27], off
	v_lshlrev_b32_e32 v28, 12, v23
	v_mov_b32_e32 v29, v3
	v_lshl_add_u64 v[4:5], v[4:5], 0, v[28:29]
	v_cvt_pk_bf16_f32 v24, v31, v33
	v_cvt_pk_bf16_f32 v25, v35, v37
	v_cvt_pk_bf16_f32 v26, v39, v41
	v_cvt_pk_bf16_f32 v27, v43, v45
	global_store_dwordx4 v[4:5], v[24:27], off
	s_waitcnt lgkmcnt(0)
	s_cbranch_execnz .LBB0_153
.LBB0_157:
	v_mov_b64_e32 v[4:5], s[6:7]
	s_load_dwordx2 s[98:99], s[0:1], 0x50
	s_mul_hi_i32 s4, s13, 0x7f807f81
	s_lshr_b32 s8, s4, 31
	s_ashr_i32 s9, s4, 12
	s_add_i32 s9, s9, s8
	s_mul_i32 s4, s9, 0xffffdfe0
	s_add_i32 s4, s13, s4
	s_mul_hi_i32 s8, s4, 0x7f807f81
	s_lshr_b32 s10, s8, 31
	s_ashr_i32 s8, s8, 7
	s_add_i32 s8, s8, s10
	s_mul_i32 s10, s8, 0x101
	s_sub_i32 s4, s4, s10
	s_lshl_b32 s4, s4, 5
	v_or_b32_e32 v26, s4, v6
	s_lshl_b32 s8, s8, 6
	v_ashrrev_i32_e32 v27, 31, v26
	v_mov_b32_e32 v23, 0
	v_or_b32_e32 v24, s8, v7
	v_cmp_gt_i32_e32 vcc, s52, v26
	v_mov_b32_e32 v25, 0
	s_waitcnt lgkmcnt(0)
	v_mov_b32_e32 v4, s98
	v_mov_b32_e32 v5, s99
	v_mad_i64_i32 v[4:5], s[10:11], s9, v21, v[4:5]
	v_lshl_add_u64 v[4:5], v[26:27], 2, v[4:5]
	s_and_saveexec_b64 s[10:11], vcc
	s_cbranch_execz .LBB0_159
	v_mad_i64_i32 v[26:27], s[54:55], v24, s53, v[4:5]
	global_load_dword v25, v[26:27], off
